# grid barrier: every waiter polls the leader arrival counter for its target value instead of the generation word (removes the last leader's round trip), on top of previous
# speedup vs baseline: 1.0046x; 1.0007x over previous
; __device__ __forceinline__ unsigned xb_ld(unsigned* p)              { return __hip_atomic_load(p, __ATOMIC_RELAXED, __HIP_MEMORY_SCOPE_AGENT); }
; __device__ __forceinline__ unsigned xb_add(unsigned* p, unsigned v) { return __hip_atomic_fetch_add(p, v, __ATOMIC_RELAXED, __HIP_MEMORY_SCOPE_AGENT); }
; #define XB_SPIN(cond, bar) do { unsigned _sp = 0; while (cond) { __builtin_amdgcn_s_sleep(1); \
;     if ((++_sp & 255u) == 0u) { if (xb_ld(&(bar)[XB_TMO])) break; if (_sp > XB_SPIN_CAP) { atomicAdd(&(bar)[XB_TMO], 1u); break; } } } } while (0)
; __device__ __forceinline__ void xcd_barrier(const XcdBarrier& b) {
;     ...
;         const unsigned old = xb_add(&bar[XB_XSUB(b.x)], 1u);
;         const unsigned gen = old / nloc;
;         if (old + 1u == (gen + 1u) * nloc) {
;             __builtin_amdgcn_fence(__ATOMIC_RELEASE, "agent");
;             asm volatile("s_waitcnt vmcnt(0)" ::: "memory");
;             const unsigned og = xb_add(&bar[XB_TOP], 1u);
;             const unsigned tg = og / nx;
;             if (og + 1u == (tg + 1u) * nx) xb_add(&bar[XB_TOPGEN], 1u);
;             else XB_SPIN(xb_ld(&bar[XB_TOPGEN]) == tg, bar);
;             __builtin_amdgcn_fence(__ATOMIC_ACQUIRE, "agent");
;             xb_add(&bar[XB_XGEN(b.x)], 1u);
;             asm volatile("s_waitcnt vmcnt(0)" ::: "memory");
;         } else {
;             XB_SPIN(xb_ld(&bar[XB_XGEN(b.x)]) <= gen, bar);
.LBB0_145:
	s_lshl_b32 s6, s33, 8
	s_add_u32 s6, s52, s6
	s_addc_u32 s7, s53, 0
	v_mov_b32_e32 v2, 0x1000
	v_mov_b32_e32 v4, 1
	global_atomic_add v4, v2, v4, s[6:7] offset:1024 sc0
	v_cvt_f32_u32_e32 v2, v3
	v_sub_u32_e32 v5, 0, v3
	v_rcp_iflag_f32_e32 v2, v2
	s_nop 0
	v_mul_f32_e32 v2, 0x4f7ffffe, v2
	v_cvt_u32_f32_e32 v2, v2
	v_mul_lo_u32 v5, v5, v2
	v_mul_hi_u32 v5, v2, v5
	v_add_u32_e32 v2, v2, v5
	s_waitcnt vmcnt(0)
	v_mul_hi_u32 v2, v4, v2
	v_mul_lo_u32 v5, v2, v3
	v_sub_u32_e32 v5, v4, v5
	v_add_u32_e32 v6, 1, v2
	v_cmp_ge_u32_e32 vcc, v5, v3
	v_add_u32_e32 v4, 1, v4
	s_nop 0
	v_cndmask_b32_e32 v2, v2, v6, vcc
	v_sub_u32_e32 v6, v5, v3
	v_cndmask_b32_e32 v5, v5, v6, vcc
	v_add_u32_e32 v6, 1, v2
	v_cmp_ge_u32_e32 vcc, v5, v3
	s_nop 1
	v_cndmask_b32_e32 v2, v2, v6, vcc
	v_mul_lo_u32 v5, v3, v2
	v_add_u32_e32 v3, v5, v3
	v_cmp_ne_u32_e32 vcc, v4, v3
	s_and_saveexec_b64 s[12:13], vcc
	s_xor_b64 s[12:13], exec, s[12:13]
	s_cbranch_execz .LBB0_159
	s_waitcnt lgkmcnt(0)
	v_add_u32_e32 v2, 1, v2
	v_mul_lo_u32 v2, v2, v1
	v_add_u32_e32 v2, -1, v2
	v_mov_b32_e32 v1, 0x3000
	global_load_dword v1, v1, s[52:53] offset:1024 sc1
	s_add_u32 s18, s52, 0x3400
	s_addc_u32 s19, s53, 0
	s_waitcnt vmcnt(0)
	v_cmp_le_u32_e32 vcc, v1, v2
	s_and_saveexec_b64 s[14:15], vcc
	s_cbranch_execz .LBB0_158
	s_mov_b32 s35, 1
	s_mov_b64 s[22:23], 0
	v_mov_b32_e32 v1, 0
	s_branch .LBB0_149

; __device__ __forceinline__ unsigned xb_ld(unsigned* p)              { return __hip_atomic_load(p, __ATOMIC_RELAXED, __HIP_MEMORY_SCOPE_AGENT); }
; __device__ __forceinline__ unsigned xb_add(unsigned* p, unsigned v) { return __hip_atomic_fetch_add(p, v, __ATOMIC_RELAXED, __HIP_MEMORY_SCOPE_AGENT); }
; #define XB_SPIN(cond, bar) do { unsigned _sp = 0; while (cond) { __builtin_amdgcn_s_sleep(1); \
;     if ((++_sp & 255u) == 0u) { if (xb_ld(&(bar)[XB_TMO])) break; if (_sp > XB_SPIN_CAP) { atomicAdd(&(bar)[XB_TMO], 1u); break; } } } } while (0)
; __device__ __forceinline__ void xcd_barrier(const XcdBarrier& b) {
;     ...
;         if (old + 1u == (gen + 1u) * nloc) {
;             __builtin_amdgcn_fence(__ATOMIC_RELEASE, "agent");
;             asm volatile("s_waitcnt vmcnt(0)" ::: "memory");
;             const unsigned og = xb_add(&bar[XB_TOP], 1u);
;             const unsigned tg = og / nx;
;             if (og + 1u == (tg + 1u) * nx) xb_add(&bar[XB_TOPGEN], 1u);
;             else XB_SPIN(xb_ld(&bar[XB_TOPGEN]) == tg, bar);
;             __builtin_amdgcn_fence(__ATOMIC_ACQUIRE, "agent");
.LBB0_162:
	s_or_b64 exec, exec, s[14:15]
	v_cvt_f32_u32_e32 v4, v1
	s_waitcnt vmcnt(0)
	v_readfirstlane_b32 s12, v3
	s_add_u32 s14, s52, 0x3500
	s_addc_u32 s15, s53, 0
	v_rcp_iflag_f32_e32 v4, v4
	v_add_u32_e32 v2, s12, v2
	v_add_u32_e32 v5, 1, v2
	s_mov_b64 s[18:19], -1
	v_mul_f32_e32 v3, 0x4f7ffffe, v4
	v_cvt_u32_f32_e32 v3, v3
	v_sub_u32_e32 v4, 0, v1
	v_mul_lo_u32 v4, v4, v3
	v_mul_hi_u32 v4, v3, v4
	v_add_u32_e32 v3, v3, v4
	v_mul_hi_u32 v3, v2, v3
	v_mul_lo_u32 v4, v3, v1
	v_sub_u32_e32 v2, v2, v4
	v_add_u32_e32 v6, 1, v3
	v_cmp_ge_u32_e32 vcc, v2, v1
	v_sub_u32_e32 v4, v2, v1
	s_nop 0
	v_cndmask_b32_e32 v3, v3, v6, vcc
	v_cndmask_b32_e32 v2, v2, v4, vcc
	v_add_u32_e32 v4, 1, v3
	v_cmp_ge_u32_e32 vcc, v2, v1
	s_nop 1
	v_cndmask_b32_e32 v4, v3, v4, vcc
	v_mul_lo_u32 v2, v1, v4
	v_add_u32_e32 v1, v2, v1
	v_cmp_ne_u32_e32 vcc, v5, v1
	v_mov_b32_e32 v4, v1
	v_mov_b64_e32 v[2:3], s[14:15]
	s_and_saveexec_b64 s[12:13], vcc
	s_cbranch_execz .LBB0_174
	v_mov_b32_e32 v1, 0
	global_load_dword v2, v1, s[14:15] offset:-256 sc1
	s_mov_b64 s[24:25], 0
	s_waitcnt vmcnt(0)
	v_cmp_lt_u32_e32 vcc, v2, v4
	s_and_saveexec_b64 s[22:23], vcc
	s_cbranch_execz .LBB0_173
	s_add_u32 s18, s52, 0x200
	s_addc_u32 s19, s53, 0
	s_mov_b32 s35, 1
	s_branch .LBB0_166

; __device__ __forceinline__ unsigned xb_ld(unsigned* p)              { return __hip_atomic_load(p, __ATOMIC_RELAXED, __HIP_MEMORY_SCOPE_AGENT); }
; __device__ __forceinline__ unsigned xb_add(unsigned* p, unsigned v) { return __hip_atomic_fetch_add(p, v, __ATOMIC_RELAXED, __HIP_MEMORY_SCOPE_AGENT); }
; #define XB_SPIN(cond, bar) do { unsigned _sp = 0; while (cond) { __builtin_amdgcn_s_sleep(1); \
;     if ((++_sp & 255u) == 0u) { if (xb_ld(&(bar)[XB_TMO])) break; if (_sp > XB_SPIN_CAP) { atomicAdd(&(bar)[XB_TMO], 1u); break; } } } } while (0)
; __device__ __forceinline__ void xcd_barrier(const XcdBarrier& b) {
;     ...
;             const unsigned og = xb_add(&bar[XB_TOP], 1u);
;             const unsigned tg = og / nx;
;             if (og + 1u == (tg + 1u) * nx) xb_add(&bar[XB_TOPGEN], 1u);
;             else XB_SPIN(xb_ld(&bar[XB_TOPGEN]) == tg, bar);
.LBB0_168:
	global_load_dword v2, v1, s[14:15] offset:-256 sc1
	s_add_i32 s35, s35, 1
	s_mov_b64 s[36:37], -1
	s_waitcnt vmcnt(0)
	v_cmp_ge_u32_e32 vcc, v2, v4
	s_orn2_b64 s[42:43], vcc, exec
	s_branch .LBB0_165

; __device__ __forceinline__ unsigned xb_ld(unsigned* p)              { return __hip_atomic_load(p, __ATOMIC_RELAXED, __HIP_MEMORY_SCOPE_AGENT); }
; __device__ __forceinline__ unsigned xb_add(unsigned* p, unsigned v) { return __hip_atomic_fetch_add(p, v, __ATOMIC_RELAXED, __HIP_MEMORY_SCOPE_AGENT); }
; #define XB_SPIN(cond, bar) do { unsigned _sp = 0; while (cond) { __builtin_amdgcn_s_sleep(1); \
;     if ((++_sp & 255u) == 0u) { if (xb_ld(&(bar)[XB_TMO])) break; if (_sp > XB_SPIN_CAP) { atomicAdd(&(bar)[XB_TMO], 1u); break; } } } } while (0)
; __device__ __forceinline__ void xcd_barrier(const XcdBarrier& b) {
;     ...
;         const unsigned old = xb_add(&bar[XB_XSUB(b.x)], 1u);
;         const unsigned gen = old / nloc;
;         if (old + 1u == (gen + 1u) * nloc) {
;             __builtin_amdgcn_fence(__ATOMIC_RELEASE, "agent");
;             asm volatile("s_waitcnt vmcnt(0)" ::: "memory");
;             const unsigned og = xb_add(&bar[XB_TOP], 1u);
;             const unsigned tg = og / nx;
;             if (og + 1u == (tg + 1u) * nx) xb_add(&bar[XB_TOPGEN], 1u);
;             else XB_SPIN(xb_ld(&bar[XB_TOPGEN]) == tg, bar);
;             __builtin_amdgcn_fence(__ATOMIC_ACQUIRE, "agent");
;             xb_add(&bar[XB_XGEN(b.x)], 1u);
;             asm volatile("s_waitcnt vmcnt(0)" ::: "memory");
;         } else {
;             XB_SPIN(xb_ld(&bar[XB_XGEN(b.x)]) <= gen, bar);
.LBB0_234:
	s_lshl_b32 s12, s33, 8
	s_add_u32 s12, s52, s12
	s_addc_u32 s13, s53, 0
	v_mov_b32_e32 v2, 0x1000
	v_mov_b32_e32 v4, 1
	global_atomic_add v4, v2, v4, s[12:13] offset:1024 sc0
	v_cvt_f32_u32_e32 v2, v3
	v_sub_u32_e32 v5, 0, v3
	v_rcp_iflag_f32_e32 v2, v2
	s_nop 0
	v_mul_f32_e32 v2, 0x4f7ffffe, v2
	v_cvt_u32_f32_e32 v2, v2
	v_mul_lo_u32 v5, v5, v2
	v_mul_hi_u32 v5, v2, v5
	v_add_u32_e32 v2, v2, v5
	s_waitcnt vmcnt(0)
	v_mul_hi_u32 v2, v4, v2
	v_mul_lo_u32 v5, v2, v3
	v_sub_u32_e32 v5, v4, v5
	v_add_u32_e32 v6, 1, v2
	v_cmp_ge_u32_e32 vcc, v5, v3
	v_add_u32_e32 v4, 1, v4
	s_nop 0
	v_cndmask_b32_e32 v2, v2, v6, vcc
	v_sub_u32_e32 v6, v5, v3
	v_cndmask_b32_e32 v5, v5, v6, vcc
	v_add_u32_e32 v6, 1, v2
	v_cmp_ge_u32_e32 vcc, v5, v3
	s_nop 1
	v_cndmask_b32_e32 v2, v2, v6, vcc
	v_mul_lo_u32 v5, v3, v2
	v_add_u32_e32 v3, v5, v3
	v_cmp_ne_u32_e32 vcc, v4, v3
	s_and_saveexec_b64 s[14:15], vcc
	s_xor_b64 s[14:15], exec, s[14:15]
	s_cbranch_execz .LBB0_248
	s_waitcnt lgkmcnt(0)
	v_add_u32_e32 v2, 1, v2
	v_mul_lo_u32 v2, v2, v1
	v_add_u32_e32 v2, -1, v2
	v_mov_b32_e32 v1, 0x3000
	global_load_dword v1, v1, s[52:53] offset:1024 sc1
	s_add_u32 s22, s52, 0x3400
	s_addc_u32 s23, s53, 0
	s_waitcnt vmcnt(0)
	v_cmp_le_u32_e32 vcc, v1, v2
	s_and_saveexec_b64 s[18:19], vcc
	s_cbranch_execz .LBB0_247
	s_mov_b32 s35, 1
	s_mov_b64 s[24:25], 0
	v_mov_b32_e32 v1, 0
	s_branch .LBB0_238

; __device__ __forceinline__ unsigned xb_ld(unsigned* p)              { return __hip_atomic_load(p, __ATOMIC_RELAXED, __HIP_MEMORY_SCOPE_AGENT); }
; __device__ __forceinline__ unsigned xb_add(unsigned* p, unsigned v) { return __hip_atomic_fetch_add(p, v, __ATOMIC_RELAXED, __HIP_MEMORY_SCOPE_AGENT); }
; #define XB_SPIN(cond, bar) do { unsigned _sp = 0; while (cond) { __builtin_amdgcn_s_sleep(1); \
;     if ((++_sp & 255u) == 0u) { if (xb_ld(&(bar)[XB_TMO])) break; if (_sp > XB_SPIN_CAP) { atomicAdd(&(bar)[XB_TMO], 1u); break; } } } } while (0)
; __device__ __forceinline__ void xcd_barrier(const XcdBarrier& b) {
;     ...
;         if (old + 1u == (gen + 1u) * nloc) {
;             __builtin_amdgcn_fence(__ATOMIC_RELEASE, "agent");
;             asm volatile("s_waitcnt vmcnt(0)" ::: "memory");
;             const unsigned og = xb_add(&bar[XB_TOP], 1u);
;             const unsigned tg = og / nx;
;             if (og + 1u == (tg + 1u) * nx) xb_add(&bar[XB_TOPGEN], 1u);
;             else XB_SPIN(xb_ld(&bar[XB_TOPGEN]) == tg, bar);
;             __builtin_amdgcn_fence(__ATOMIC_ACQUIRE, "agent");
.LBB0_251:
	s_or_b64 exec, exec, s[18:19]
	v_cvt_f32_u32_e32 v4, v1
	s_waitcnt vmcnt(0)
	v_readfirstlane_b32 s14, v3
	s_add_u32 s18, s52, 0x3500
	s_addc_u32 s19, s53, 0
	v_rcp_iflag_f32_e32 v4, v4
	v_add_u32_e32 v2, s14, v2
	v_add_u32_e32 v5, 1, v2
	s_mov_b64 s[22:23], -1
	v_mul_f32_e32 v3, 0x4f7ffffe, v4
	v_cvt_u32_f32_e32 v3, v3
	v_sub_u32_e32 v4, 0, v1
	v_mul_lo_u32 v4, v4, v3
	v_mul_hi_u32 v4, v3, v4
	v_add_u32_e32 v3, v3, v4
	v_mul_hi_u32 v3, v2, v3
	v_mul_lo_u32 v4, v3, v1
	v_sub_u32_e32 v2, v2, v4
	v_add_u32_e32 v6, 1, v3
	v_cmp_ge_u32_e32 vcc, v2, v1
	v_sub_u32_e32 v4, v2, v1
	s_nop 0
	v_cndmask_b32_e32 v3, v3, v6, vcc
	v_cndmask_b32_e32 v2, v2, v4, vcc
	v_add_u32_e32 v4, 1, v3
	v_cmp_ge_u32_e32 vcc, v2, v1
	s_nop 1
	v_cndmask_b32_e32 v4, v3, v4, vcc
	v_mul_lo_u32 v2, v1, v4
	v_add_u32_e32 v1, v2, v1
	v_cmp_ne_u32_e32 vcc, v5, v1
	v_mov_b32_e32 v4, v1
	v_mov_b64_e32 v[2:3], s[18:19]
	s_and_saveexec_b64 s[14:15], vcc
	s_cbranch_execz .LBB0_263
	v_mov_b32_e32 v1, 0
	global_load_dword v2, v1, s[18:19] offset:-256 sc1
	s_mov_b64 s[26:27], 0
	s_waitcnt vmcnt(0)
	v_cmp_lt_u32_e32 vcc, v2, v4
	s_and_saveexec_b64 s[24:25], vcc
	s_cbranch_execz .LBB0_262
	s_add_u32 s22, s52, 0x200
	s_addc_u32 s23, s53, 0
	s_mov_b32 s35, 1
	s_branch .LBB0_255

; __device__ __forceinline__ unsigned xb_ld(unsigned* p)              { return __hip_atomic_load(p, __ATOMIC_RELAXED, __HIP_MEMORY_SCOPE_AGENT); }
; __device__ __forceinline__ unsigned xb_add(unsigned* p, unsigned v) { return __hip_atomic_fetch_add(p, v, __ATOMIC_RELAXED, __HIP_MEMORY_SCOPE_AGENT); }
; #define XB_SPIN(cond, bar) do { unsigned _sp = 0; while (cond) { __builtin_amdgcn_s_sleep(1); \
;     if ((++_sp & 255u) == 0u) { if (xb_ld(&(bar)[XB_TMO])) break; if (_sp > XB_SPIN_CAP) { atomicAdd(&(bar)[XB_TMO], 1u); break; } } } } while (0)
; __device__ __forceinline__ void xcd_barrier(const XcdBarrier& b) {
;     ...
;             const unsigned og = xb_add(&bar[XB_TOP], 1u);
;             const unsigned tg = og / nx;
;             if (og + 1u == (tg + 1u) * nx) xb_add(&bar[XB_TOPGEN], 1u);
;             else XB_SPIN(xb_ld(&bar[XB_TOPGEN]) == tg, bar);
.LBB0_257:
	global_load_dword v2, v1, s[18:19] offset:-256 sc1
	s_add_i32 s35, s35, 1
	s_mov_b64 s[40:41], -1
	s_waitcnt vmcnt(0)
	v_cmp_ge_u32_e32 vcc, v2, v4
	s_orn2_b64 s[48:49], vcc, exec
	s_branch .LBB0_254

; __device__ __forceinline__ unsigned xb_ld(unsigned* p)              { return __hip_atomic_load(p, __ATOMIC_RELAXED, __HIP_MEMORY_SCOPE_AGENT); }
; __device__ __forceinline__ unsigned xb_add(unsigned* p, unsigned v) { return __hip_atomic_fetch_add(p, v, __ATOMIC_RELAXED, __HIP_MEMORY_SCOPE_AGENT); }
; #define XB_SPIN(cond, bar) do { unsigned _sp = 0; while (cond) { __builtin_amdgcn_s_sleep(1); \
;     if ((++_sp & 255u) == 0u) { if (xb_ld(&(bar)[XB_TMO])) break; if (_sp > XB_SPIN_CAP) { atomicAdd(&(bar)[XB_TMO], 1u); break; } } } } while (0)
; __device__ __forceinline__ void xcd_barrier(const XcdBarrier& b) {
;     ...
;         const unsigned old = xb_add(&bar[XB_XSUB(b.x)], 1u);
;         const unsigned gen = old / nloc;
;         if (old + 1u == (gen + 1u) * nloc) {
;             __builtin_amdgcn_fence(__ATOMIC_RELEASE, "agent");
;             asm volatile("s_waitcnt vmcnt(0)" ::: "memory");
;             const unsigned og = xb_add(&bar[XB_TOP], 1u);
;             const unsigned tg = og / nx;
;             if (og + 1u == (tg + 1u) * nx) xb_add(&bar[XB_TOPGEN], 1u);
;             else XB_SPIN(xb_ld(&bar[XB_TOPGEN]) == tg, bar);
;             __builtin_amdgcn_fence(__ATOMIC_ACQUIRE, "agent");
;             xb_add(&bar[XB_XGEN(b.x)], 1u);
;             asm volatile("s_waitcnt vmcnt(0)" ::: "memory");
;         } else {
;             XB_SPIN(xb_ld(&bar[XB_XGEN(b.x)]) <= gen, bar);
.LBB0_309:
	s_lshl_b32 s12, s33, 8
	s_add_u32 s12, s52, s12
	s_addc_u32 s13, s53, 0
	v_mov_b32_e32 v2, 0x1000
	v_mov_b32_e32 v4, 1
	global_atomic_add v4, v2, v4, s[12:13] offset:1024 sc0
	v_cvt_f32_u32_e32 v2, v3
	v_sub_u32_e32 v5, 0, v3
	v_rcp_iflag_f32_e32 v2, v2
	s_nop 0
	v_mul_f32_e32 v2, 0x4f7ffffe, v2
	v_cvt_u32_f32_e32 v2, v2
	v_mul_lo_u32 v5, v5, v2
	v_mul_hi_u32 v5, v2, v5
	v_add_u32_e32 v2, v2, v5
	s_waitcnt vmcnt(0)
	v_mul_hi_u32 v2, v4, v2
	v_mul_lo_u32 v5, v2, v3
	v_sub_u32_e32 v5, v4, v5
	v_add_u32_e32 v6, 1, v2
	v_cmp_ge_u32_e32 vcc, v5, v3
	v_add_u32_e32 v4, 1, v4
	s_nop 0
	v_cndmask_b32_e32 v2, v2, v6, vcc
	v_sub_u32_e32 v6, v5, v3
	v_cndmask_b32_e32 v5, v5, v6, vcc
	v_add_u32_e32 v6, 1, v2
	v_cmp_ge_u32_e32 vcc, v5, v3
	s_nop 1
	v_cndmask_b32_e32 v2, v2, v6, vcc
	v_mul_lo_u32 v5, v3, v2
	v_add_u32_e32 v3, v5, v3
	v_cmp_ne_u32_e32 vcc, v4, v3
	s_and_saveexec_b64 s[14:15], vcc
	s_xor_b64 s[14:15], exec, s[14:15]
	s_cbranch_execz .LBB0_323
	s_waitcnt lgkmcnt(0)
	v_add_u32_e32 v2, 1, v2
	v_mul_lo_u32 v2, v2, v1
	v_add_u32_e32 v2, -1, v2
	v_mov_b32_e32 v1, 0x3000
	global_load_dword v1, v1, s[52:53] offset:1024 sc1
	s_add_u32 s22, s52, 0x3400
	s_addc_u32 s23, s53, 0
	s_waitcnt vmcnt(0)
	v_cmp_le_u32_e32 vcc, v1, v2
	s_and_saveexec_b64 s[18:19], vcc
	s_cbranch_execz .LBB0_322
	s_mov_b32 s36, 1
	s_mov_b64 s[24:25], 0
	v_mov_b32_e32 v1, 0
	s_branch .LBB0_313

; __device__ __forceinline__ unsigned xb_ld(unsigned* p)              { return __hip_atomic_load(p, __ATOMIC_RELAXED, __HIP_MEMORY_SCOPE_AGENT); }
; __device__ __forceinline__ unsigned xb_add(unsigned* p, unsigned v) { return __hip_atomic_fetch_add(p, v, __ATOMIC_RELAXED, __HIP_MEMORY_SCOPE_AGENT); }
; #define XB_SPIN(cond, bar) do { unsigned _sp = 0; while (cond) { __builtin_amdgcn_s_sleep(1); \
;     if ((++_sp & 255u) == 0u) { if (xb_ld(&(bar)[XB_TMO])) break; if (_sp > XB_SPIN_CAP) { atomicAdd(&(bar)[XB_TMO], 1u); break; } } } } while (0)
; __device__ __forceinline__ void xcd_barrier(const XcdBarrier& b) {
;     ...
;         if (old + 1u == (gen + 1u) * nloc) {
;             __builtin_amdgcn_fence(__ATOMIC_RELEASE, "agent");
;             asm volatile("s_waitcnt vmcnt(0)" ::: "memory");
;             const unsigned og = xb_add(&bar[XB_TOP], 1u);
;             const unsigned tg = og / nx;
;             if (og + 1u == (tg + 1u) * nx) xb_add(&bar[XB_TOPGEN], 1u);
;             else XB_SPIN(xb_ld(&bar[XB_TOPGEN]) == tg, bar);
;             __builtin_amdgcn_fence(__ATOMIC_ACQUIRE, "agent");
.LBB0_326:
	s_or_b64 exec, exec, s[18:19]
	v_cvt_f32_u32_e32 v4, v1
	s_waitcnt vmcnt(0)
	v_readfirstlane_b32 s14, v3
	s_add_u32 s18, s52, 0x3500
	s_addc_u32 s19, s53, 0
	v_rcp_iflag_f32_e32 v4, v4
	v_add_u32_e32 v2, s14, v2
	v_add_u32_e32 v5, 1, v2
	s_mov_b64 s[22:23], -1
	v_mul_f32_e32 v3, 0x4f7ffffe, v4
	v_cvt_u32_f32_e32 v3, v3
	v_sub_u32_e32 v4, 0, v1
	v_mul_lo_u32 v4, v4, v3
	v_mul_hi_u32 v4, v3, v4
	v_add_u32_e32 v3, v3, v4
	v_mul_hi_u32 v3, v2, v3
	v_mul_lo_u32 v4, v3, v1
	v_sub_u32_e32 v2, v2, v4
	v_add_u32_e32 v6, 1, v3
	v_cmp_ge_u32_e32 vcc, v2, v1
	v_sub_u32_e32 v4, v2, v1
	s_nop 0
	v_cndmask_b32_e32 v3, v3, v6, vcc
	v_cndmask_b32_e32 v2, v2, v4, vcc
	v_add_u32_e32 v4, 1, v3
	v_cmp_ge_u32_e32 vcc, v2, v1
	s_nop 1
	v_cndmask_b32_e32 v4, v3, v4, vcc
	v_mul_lo_u32 v2, v1, v4
	v_add_u32_e32 v1, v2, v1
	v_cmp_ne_u32_e32 vcc, v5, v1
	v_mov_b32_e32 v4, v1
	v_mov_b64_e32 v[2:3], s[18:19]
	s_and_saveexec_b64 s[14:15], vcc
	s_cbranch_execz .LBB0_338
	v_mov_b32_e32 v1, 0
	global_load_dword v2, v1, s[18:19] offset:-256 sc1
	s_mov_b64 s[26:27], 0
	s_waitcnt vmcnt(0)
	v_cmp_lt_u32_e32 vcc, v2, v4
	s_and_saveexec_b64 s[24:25], vcc
	s_cbranch_execz .LBB0_337
	s_add_u32 s22, s52, 0x200
	s_addc_u32 s23, s53, 0
	s_mov_b32 s38, 1
	s_branch .LBB0_330

; __device__ __forceinline__ unsigned xb_ld(unsigned* p)              { return __hip_atomic_load(p, __ATOMIC_RELAXED, __HIP_MEMORY_SCOPE_AGENT); }
; __device__ __forceinline__ unsigned xb_add(unsigned* p, unsigned v) { return __hip_atomic_fetch_add(p, v, __ATOMIC_RELAXED, __HIP_MEMORY_SCOPE_AGENT); }
; #define XB_SPIN(cond, bar) do { unsigned _sp = 0; while (cond) { __builtin_amdgcn_s_sleep(1); \
;     if ((++_sp & 255u) == 0u) { if (xb_ld(&(bar)[XB_TMO])) break; if (_sp > XB_SPIN_CAP) { atomicAdd(&(bar)[XB_TMO], 1u); break; } } } } while (0)
; __device__ __forceinline__ void xcd_barrier(const XcdBarrier& b) {
;     ...
;             const unsigned og = xb_add(&bar[XB_TOP], 1u);
;             const unsigned tg = og / nx;
;             if (og + 1u == (tg + 1u) * nx) xb_add(&bar[XB_TOPGEN], 1u);
;             else XB_SPIN(xb_ld(&bar[XB_TOPGEN]) == tg, bar);
.LBB0_332:
	global_load_dword v2, v1, s[18:19] offset:-256 sc1
	s_add_i32 s38, s38, 1
	s_mov_b64 s[30:31], -1
	s_waitcnt vmcnt(0)
	v_cmp_ge_u32_e32 vcc, v2, v4
	s_orn2_b64 s[36:37], vcc, exec
	s_branch .LBB0_329

; __device__ __forceinline__ unsigned xb_ld(unsigned* p)              { return __hip_atomic_load(p, __ATOMIC_RELAXED, __HIP_MEMORY_SCOPE_AGENT); }
; __device__ __forceinline__ unsigned xb_add(unsigned* p, unsigned v) { return __hip_atomic_fetch_add(p, v, __ATOMIC_RELAXED, __HIP_MEMORY_SCOPE_AGENT); }
; #define XB_SPIN(cond, bar) do { unsigned _sp = 0; while (cond) { __builtin_amdgcn_s_sleep(1); \
;     if ((++_sp & 255u) == 0u) { if (xb_ld(&(bar)[XB_TMO])) break; if (_sp > XB_SPIN_CAP) { atomicAdd(&(bar)[XB_TMO], 1u); break; } } } } while (0)
; __device__ __forceinline__ void xcd_barrier(const XcdBarrier& b) {
;     ...
;         const unsigned old = xb_add(&bar[XB_XSUB(b.x)], 1u);
;         const unsigned gen = old / nloc;
;         if (old + 1u == (gen + 1u) * nloc) {
;             __builtin_amdgcn_fence(__ATOMIC_RELEASE, "agent");
;             asm volatile("s_waitcnt vmcnt(0)" ::: "memory");
;             const unsigned og = xb_add(&bar[XB_TOP], 1u);
;             const unsigned tg = og / nx;
;             if (og + 1u == (tg + 1u) * nx) xb_add(&bar[XB_TOPGEN], 1u);
;             else XB_SPIN(xb_ld(&bar[XB_TOPGEN]) == tg, bar);
;             __builtin_amdgcn_fence(__ATOMIC_ACQUIRE, "agent");
;             xb_add(&bar[XB_XGEN(b.x)], 1u);
;             asm volatile("s_waitcnt vmcnt(0)" ::: "memory");
;         } else {
;             XB_SPIN(xb_ld(&bar[XB_XGEN(b.x)]) <= gen, bar);
.LBB0_402:
	s_lshl_b32 s12, s33, 8
	s_add_u32 s12, s52, s12
	s_addc_u32 s13, s53, 0
	v_mov_b32_e32 v2, 0x1000
	v_mov_b32_e32 v4, 1
	global_atomic_add v4, v2, v4, s[12:13] offset:1024 sc0
	v_cvt_f32_u32_e32 v2, v3
	v_sub_u32_e32 v5, 0, v3
	v_rcp_iflag_f32_e32 v2, v2
	s_nop 0
	v_mul_f32_e32 v2, 0x4f7ffffe, v2
	v_cvt_u32_f32_e32 v2, v2
	v_mul_lo_u32 v5, v5, v2
	v_mul_hi_u32 v5, v2, v5
	v_add_u32_e32 v2, v2, v5
	s_waitcnt vmcnt(0)
	v_mul_hi_u32 v2, v4, v2
	v_mul_lo_u32 v5, v2, v3
	v_sub_u32_e32 v5, v4, v5
	v_add_u32_e32 v6, 1, v2
	v_cmp_ge_u32_e32 vcc, v5, v3
	v_add_u32_e32 v4, 1, v4
	s_nop 0
	v_cndmask_b32_e32 v2, v2, v6, vcc
	v_sub_u32_e32 v6, v5, v3
	v_cndmask_b32_e32 v5, v5, v6, vcc
	v_add_u32_e32 v6, 1, v2
	v_cmp_ge_u32_e32 vcc, v5, v3
	s_nop 1
	v_cndmask_b32_e32 v2, v2, v6, vcc
	v_mul_lo_u32 v5, v3, v2
	v_add_u32_e32 v3, v5, v3
	v_cmp_ne_u32_e32 vcc, v4, v3
	s_and_saveexec_b64 s[14:15], vcc
	s_xor_b64 s[14:15], exec, s[14:15]
	s_cbranch_execz .LBB0_416
	s_waitcnt lgkmcnt(0)
	v_add_u32_e32 v2, 1, v2
	v_mul_lo_u32 v2, v2, v1
	v_add_u32_e32 v2, -1, v2
	v_mov_b32_e32 v1, 0x3000
	global_load_dword v1, v1, s[52:53] offset:1024 sc1
	s_add_u32 s18, s52, 0x3400
	s_addc_u32 s19, s53, 0
	s_waitcnt vmcnt(0)
	v_cmp_le_u32_e32 vcc, v1, v2
	s_and_saveexec_b64 s[16:17], vcc
	s_cbranch_execz .LBB0_415
	s_mov_b32 s30, 1
	s_mov_b64 s[20:21], 0
	v_mov_b32_e32 v1, 0
	s_branch .LBB0_406

; __device__ __forceinline__ unsigned xb_ld(unsigned* p)              { return __hip_atomic_load(p, __ATOMIC_RELAXED, __HIP_MEMORY_SCOPE_AGENT); }
; __device__ __forceinline__ unsigned xb_add(unsigned* p, unsigned v) { return __hip_atomic_fetch_add(p, v, __ATOMIC_RELAXED, __HIP_MEMORY_SCOPE_AGENT); }
; #define XB_SPIN(cond, bar) do { unsigned _sp = 0; while (cond) { __builtin_amdgcn_s_sleep(1); \
;     if ((++_sp & 255u) == 0u) { if (xb_ld(&(bar)[XB_TMO])) break; if (_sp > XB_SPIN_CAP) { atomicAdd(&(bar)[XB_TMO], 1u); break; } } } } while (0)
; __device__ __forceinline__ void xcd_barrier(const XcdBarrier& b) {
;     ...
;         if (old + 1u == (gen + 1u) * nloc) {
;             __builtin_amdgcn_fence(__ATOMIC_RELEASE, "agent");
;             asm volatile("s_waitcnt vmcnt(0)" ::: "memory");
;             const unsigned og = xb_add(&bar[XB_TOP], 1u);
;             const unsigned tg = og / nx;
;             if (og + 1u == (tg + 1u) * nx) xb_add(&bar[XB_TOPGEN], 1u);
;             else XB_SPIN(xb_ld(&bar[XB_TOPGEN]) == tg, bar);
;             __builtin_amdgcn_fence(__ATOMIC_ACQUIRE, "agent");
.LBB0_419:
	s_or_b64 exec, exec, s[16:17]
	v_cvt_f32_u32_e32 v4, v1
	s_waitcnt vmcnt(0)
	v_readfirstlane_b32 s14, v3
	s_add_u32 s16, s52, 0x3500
	s_addc_u32 s17, s53, 0
	v_rcp_iflag_f32_e32 v4, v4
	v_add_u32_e32 v2, s14, v2
	v_add_u32_e32 v5, 1, v2
	s_mov_b64 s[18:19], -1
	v_mul_f32_e32 v3, 0x4f7ffffe, v4
	v_cvt_u32_f32_e32 v3, v3
	v_sub_u32_e32 v4, 0, v1
	v_mul_lo_u32 v4, v4, v3
	v_mul_hi_u32 v4, v3, v4
	v_add_u32_e32 v3, v3, v4
	v_mul_hi_u32 v3, v2, v3
	v_mul_lo_u32 v4, v3, v1
	v_sub_u32_e32 v2, v2, v4
	v_add_u32_e32 v6, 1, v3
	v_cmp_ge_u32_e32 vcc, v2, v1
	v_sub_u32_e32 v4, v2, v1
	s_nop 0
	v_cndmask_b32_e32 v3, v3, v6, vcc
	v_cndmask_b32_e32 v2, v2, v4, vcc
	v_add_u32_e32 v4, 1, v3
	v_cmp_ge_u32_e32 vcc, v2, v1
	s_nop 1
	v_cndmask_b32_e32 v4, v3, v4, vcc
	v_mul_lo_u32 v2, v1, v4
	v_add_u32_e32 v1, v2, v1
	v_cmp_ne_u32_e32 vcc, v5, v1
	v_mov_b32_e32 v4, v1
	v_mov_b64_e32 v[2:3], s[16:17]
	s_and_saveexec_b64 s[14:15], vcc
	s_cbranch_execz .LBB0_431
	v_mov_b32_e32 v1, 0
	global_load_dword v2, v1, s[16:17] offset:-256 sc1
	s_mov_b64 s[22:23], 0
	s_waitcnt vmcnt(0)
	v_cmp_lt_u32_e32 vcc, v2, v4
	s_and_saveexec_b64 s[20:21], vcc
	s_cbranch_execz .LBB0_430
	s_add_u32 s18, s52, 0x200
	s_addc_u32 s19, s53, 0
	s_mov_b32 s34, 1
	s_branch .LBB0_423

; __device__ __forceinline__ unsigned xb_ld(unsigned* p)              { return __hip_atomic_load(p, __ATOMIC_RELAXED, __HIP_MEMORY_SCOPE_AGENT); }
; __device__ __forceinline__ unsigned xb_add(unsigned* p, unsigned v) { return __hip_atomic_fetch_add(p, v, __ATOMIC_RELAXED, __HIP_MEMORY_SCOPE_AGENT); }
; #define XB_SPIN(cond, bar) do { unsigned _sp = 0; while (cond) { __builtin_amdgcn_s_sleep(1); \
;     if ((++_sp & 255u) == 0u) { if (xb_ld(&(bar)[XB_TMO])) break; if (_sp > XB_SPIN_CAP) { atomicAdd(&(bar)[XB_TMO], 1u); break; } } } } while (0)
; __device__ __forceinline__ void xcd_barrier(const XcdBarrier& b) {
;     ...
;             const unsigned og = xb_add(&bar[XB_TOP], 1u);
;             const unsigned tg = og / nx;
;             if (og + 1u == (tg + 1u) * nx) xb_add(&bar[XB_TOPGEN], 1u);
;             else XB_SPIN(xb_ld(&bar[XB_TOPGEN]) == tg, bar);
.LBB0_425:
	global_load_dword v2, v1, s[16:17] offset:-256 sc1
	s_add_i32 s34, s34, 1
	s_mov_b64 s[26:27], -1
	s_waitcnt vmcnt(0)
	v_cmp_ge_u32_e32 vcc, v2, v4
	s_orn2_b64 s[30:31], vcc, exec
	s_branch .LBB0_422

; __device__ __forceinline__ unsigned xb_ld(unsigned* p)              { return __hip_atomic_load(p, __ATOMIC_RELAXED, __HIP_MEMORY_SCOPE_AGENT); }
; __device__ __forceinline__ unsigned xb_add(unsigned* p, unsigned v) { return __hip_atomic_fetch_add(p, v, __ATOMIC_RELAXED, __HIP_MEMORY_SCOPE_AGENT); }
; #define XB_SPIN(cond, bar) do { unsigned _sp = 0; while (cond) { __builtin_amdgcn_s_sleep(1); \
;     if ((++_sp & 255u) == 0u) { if (xb_ld(&(bar)[XB_TMO])) break; if (_sp > XB_SPIN_CAP) { atomicAdd(&(bar)[XB_TMO], 1u); break; } } } } while (0)
; __device__ __forceinline__ void xcd_barrier(const XcdBarrier& b) {
;     ...
;         const unsigned old = xb_add(&bar[XB_XSUB(b.x)], 1u);
;         const unsigned gen = old / nloc;
;         if (old + 1u == (gen + 1u) * nloc) {
;             __builtin_amdgcn_fence(__ATOMIC_RELEASE, "agent");
;             asm volatile("s_waitcnt vmcnt(0)" ::: "memory");
;             const unsigned og = xb_add(&bar[XB_TOP], 1u);
;             const unsigned tg = og / nx;
;             if (og + 1u == (tg + 1u) * nx) xb_add(&bar[XB_TOPGEN], 1u);
;             else XB_SPIN(xb_ld(&bar[XB_TOPGEN]) == tg, bar);
;             __builtin_amdgcn_fence(__ATOMIC_ACQUIRE, "agent");
;             xb_add(&bar[XB_XGEN(b.x)], 1u);
;             asm volatile("s_waitcnt vmcnt(0)" ::: "memory");
;         } else {
;             XB_SPIN(xb_ld(&bar[XB_XGEN(b.x)]) <= gen, bar);
.LBB0_503:
	s_lshl_b32 s8, s33, 8
	s_add_u32 s8, s52, s8
	s_addc_u32 s9, s53, 0
	v_mov_b32_e32 v2, 0x1000
	v_mov_b32_e32 v4, 1
	global_atomic_add v4, v2, v4, s[8:9] offset:1024 sc0
	v_cvt_f32_u32_e32 v2, v3
	v_sub_u32_e32 v5, 0, v3
	v_rcp_iflag_f32_e32 v2, v2
	s_nop 0
	v_mul_f32_e32 v2, 0x4f7ffffe, v2
	v_cvt_u32_f32_e32 v2, v2
	v_mul_lo_u32 v5, v5, v2
	v_mul_hi_u32 v5, v2, v5
	v_add_u32_e32 v2, v2, v5
	s_waitcnt vmcnt(0)
	v_mul_hi_u32 v2, v4, v2
	v_mul_lo_u32 v5, v2, v3
	v_sub_u32_e32 v5, v4, v5
	v_add_u32_e32 v6, 1, v2
	v_cmp_ge_u32_e32 vcc, v5, v3
	v_add_u32_e32 v4, 1, v4
	s_nop 0
	v_cndmask_b32_e32 v2, v2, v6, vcc
	v_sub_u32_e32 v6, v5, v3
	v_cndmask_b32_e32 v5, v5, v6, vcc
	v_add_u32_e32 v6, 1, v2
	v_cmp_ge_u32_e32 vcc, v5, v3
	s_nop 1
	v_cndmask_b32_e32 v2, v2, v6, vcc
	v_mul_lo_u32 v5, v3, v2
	v_add_u32_e32 v3, v5, v3
	v_cmp_ne_u32_e32 vcc, v4, v3
	s_and_saveexec_b64 s[10:11], vcc
	s_xor_b64 s[10:11], exec, s[10:11]
	s_cbranch_execz .LBB0_517
	s_waitcnt lgkmcnt(0)
	v_add_u32_e32 v2, 1, v2
	v_mul_lo_u32 v2, v2, v1
	v_add_u32_e32 v2, -1, v2
	v_mov_b32_e32 v1, 0x3000
	global_load_dword v1, v1, s[52:53] offset:1024 sc1
	s_add_u32 s14, s52, 0x3400
	s_addc_u32 s15, s53, 0
	s_waitcnt vmcnt(0)
	v_cmp_le_u32_e32 vcc, v1, v2
	s_and_saveexec_b64 s[12:13], vcc
	s_cbranch_execz .LBB0_516
	s_mov_b32 s26, 1
	s_mov_b64 s[16:17], 0
	v_mov_b32_e32 v1, 0
	s_branch .LBB0_507

; __device__ __forceinline__ unsigned xb_ld(unsigned* p)              { return __hip_atomic_load(p, __ATOMIC_RELAXED, __HIP_MEMORY_SCOPE_AGENT); }
; __device__ __forceinline__ unsigned xb_add(unsigned* p, unsigned v) { return __hip_atomic_fetch_add(p, v, __ATOMIC_RELAXED, __HIP_MEMORY_SCOPE_AGENT); }
; #define XB_SPIN(cond, bar) do { unsigned _sp = 0; while (cond) { __builtin_amdgcn_s_sleep(1); \
;     if ((++_sp & 255u) == 0u) { if (xb_ld(&(bar)[XB_TMO])) break; if (_sp > XB_SPIN_CAP) { atomicAdd(&(bar)[XB_TMO], 1u); break; } } } } while (0)
; __device__ __forceinline__ void xcd_barrier(const XcdBarrier& b) {
;     ...
;         if (old + 1u == (gen + 1u) * nloc) {
;             __builtin_amdgcn_fence(__ATOMIC_RELEASE, "agent");
;             asm volatile("s_waitcnt vmcnt(0)" ::: "memory");
;             const unsigned og = xb_add(&bar[XB_TOP], 1u);
;             const unsigned tg = og / nx;
;             if (og + 1u == (tg + 1u) * nx) xb_add(&bar[XB_TOPGEN], 1u);
;             else XB_SPIN(xb_ld(&bar[XB_TOPGEN]) == tg, bar);
;             __builtin_amdgcn_fence(__ATOMIC_ACQUIRE, "agent");
.LBB0_520:
	s_or_b64 exec, exec, s[12:13]
	v_cvt_f32_u32_e32 v4, v1
	s_waitcnt vmcnt(0)
	v_readfirstlane_b32 s10, v3
	s_add_u32 s12, s52, 0x3500
	s_addc_u32 s13, s53, 0
	v_rcp_iflag_f32_e32 v4, v4
	v_add_u32_e32 v2, s10, v2
	v_add_u32_e32 v5, 1, v2
	s_mov_b64 s[14:15], -1
	v_mul_f32_e32 v3, 0x4f7ffffe, v4
	v_cvt_u32_f32_e32 v3, v3
	v_sub_u32_e32 v4, 0, v1
	v_mul_lo_u32 v4, v4, v3
	v_mul_hi_u32 v4, v3, v4
	v_add_u32_e32 v3, v3, v4
	v_mul_hi_u32 v3, v2, v3
	v_mul_lo_u32 v4, v3, v1
	v_sub_u32_e32 v2, v2, v4
	v_add_u32_e32 v6, 1, v3
	v_cmp_ge_u32_e32 vcc, v2, v1
	v_sub_u32_e32 v4, v2, v1
	s_nop 0
	v_cndmask_b32_e32 v3, v3, v6, vcc
	v_cndmask_b32_e32 v2, v2, v4, vcc
	v_add_u32_e32 v4, 1, v3
	v_cmp_ge_u32_e32 vcc, v2, v1
	s_nop 1
	v_cndmask_b32_e32 v4, v3, v4, vcc
	v_mul_lo_u32 v2, v1, v4
	v_add_u32_e32 v1, v2, v1
	v_cmp_ne_u32_e32 vcc, v5, v1
	v_mov_b32_e32 v4, v1
	v_mov_b64_e32 v[2:3], s[12:13]
	s_and_saveexec_b64 s[10:11], vcc
	s_cbranch_execz .LBB0_532
	v_mov_b32_e32 v1, 0
	global_load_dword v2, v1, s[12:13] offset:-256 sc1
	s_mov_b64 s[18:19], 0
	s_waitcnt vmcnt(0)
	v_cmp_lt_u32_e32 vcc, v2, v4
	s_and_saveexec_b64 s[16:17], vcc
	s_cbranch_execz .LBB0_531
	s_add_u32 s14, s52, 0x200
	s_addc_u32 s15, s53, 0
	s_mov_b32 s28, 1
	s_branch .LBB0_524

; __device__ __forceinline__ unsigned xb_ld(unsigned* p)              { return __hip_atomic_load(p, __ATOMIC_RELAXED, __HIP_MEMORY_SCOPE_AGENT); }
; __device__ __forceinline__ unsigned xb_add(unsigned* p, unsigned v) { return __hip_atomic_fetch_add(p, v, __ATOMIC_RELAXED, __HIP_MEMORY_SCOPE_AGENT); }
; #define XB_SPIN(cond, bar) do { unsigned _sp = 0; while (cond) { __builtin_amdgcn_s_sleep(1); \
;     if ((++_sp & 255u) == 0u) { if (xb_ld(&(bar)[XB_TMO])) break; if (_sp > XB_SPIN_CAP) { atomicAdd(&(bar)[XB_TMO], 1u); break; } } } } while (0)
; __device__ __forceinline__ void xcd_barrier(const XcdBarrier& b) {
;     ...
;             const unsigned og = xb_add(&bar[XB_TOP], 1u);
;             const unsigned tg = og / nx;
;             if (og + 1u == (tg + 1u) * nx) xb_add(&bar[XB_TOPGEN], 1u);
;             else XB_SPIN(xb_ld(&bar[XB_TOPGEN]) == tg, bar);
.LBB0_526:
	global_load_dword v2, v1, s[12:13] offset:-256 sc1
	s_add_i32 s28, s28, 1
	s_mov_b64 s[22:23], -1
	s_waitcnt vmcnt(0)
	v_cmp_ge_u32_e32 vcc, v2, v4
	s_orn2_b64 s[26:27], vcc, exec
	s_branch .LBB0_523

; __device__ __forceinline__ unsigned xb_ld(unsigned* p)              { return __hip_atomic_load(p, __ATOMIC_RELAXED, __HIP_MEMORY_SCOPE_AGENT); }
; __device__ __forceinline__ unsigned xb_add(unsigned* p, unsigned v) { return __hip_atomic_fetch_add(p, v, __ATOMIC_RELAXED, __HIP_MEMORY_SCOPE_AGENT); }
; #define XB_SPIN(cond, bar) do { unsigned _sp = 0; while (cond) { __builtin_amdgcn_s_sleep(1); \
;     if ((++_sp & 255u) == 0u) { if (xb_ld(&(bar)[XB_TMO])) break; if (_sp > XB_SPIN_CAP) { atomicAdd(&(bar)[XB_TMO], 1u); break; } } } } while (0)
; __device__ __forceinline__ void xcd_barrier(const XcdBarrier& b) {
;     ...
;         const unsigned old = xb_add(&bar[XB_XSUB(b.x)], 1u);
;         const unsigned gen = old / nloc;
;         if (old + 1u == (gen + 1u) * nloc) {
;             __builtin_amdgcn_fence(__ATOMIC_RELEASE, "agent");
;             asm volatile("s_waitcnt vmcnt(0)" ::: "memory");
;             const unsigned og = xb_add(&bar[XB_TOP], 1u);
;             const unsigned tg = og / nx;
;             if (og + 1u == (tg + 1u) * nx) xb_add(&bar[XB_TOPGEN], 1u);
;             else XB_SPIN(xb_ld(&bar[XB_TOPGEN]) == tg, bar);
;             __builtin_amdgcn_fence(__ATOMIC_ACQUIRE, "agent");
;             xb_add(&bar[XB_XGEN(b.x)], 1u);
;             asm volatile("s_waitcnt vmcnt(0)" ::: "memory");
;         } else {
;             XB_SPIN(xb_ld(&bar[XB_XGEN(b.x)]) <= gen, bar);
.LBB0_574:
	s_lshl_b32 s6, s33, 8
	s_add_u32 s6, s52, s6
	s_addc_u32 s7, s53, 0
	v_mov_b32_e32 v2, 0x1000
	v_mov_b32_e32 v4, 1
	global_atomic_add v4, v2, v4, s[6:7] offset:1024 sc0
	v_cvt_f32_u32_e32 v2, v3
	v_sub_u32_e32 v5, 0, v3
	v_rcp_iflag_f32_e32 v2, v2
	s_nop 0
	v_mul_f32_e32 v2, 0x4f7ffffe, v2
	v_cvt_u32_f32_e32 v2, v2
	v_mul_lo_u32 v5, v5, v2
	v_mul_hi_u32 v5, v2, v5
	v_add_u32_e32 v2, v2, v5
	s_waitcnt vmcnt(0)
	v_mul_hi_u32 v2, v4, v2
	v_mul_lo_u32 v5, v2, v3
	v_sub_u32_e32 v5, v4, v5
	v_add_u32_e32 v6, 1, v2
	v_cmp_ge_u32_e32 vcc, v5, v3
	v_add_u32_e32 v4, 1, v4
	s_nop 0
	v_cndmask_b32_e32 v2, v2, v6, vcc
	v_sub_u32_e32 v6, v5, v3
	v_cndmask_b32_e32 v5, v5, v6, vcc
	v_add_u32_e32 v6, 1, v2
	v_cmp_ge_u32_e32 vcc, v5, v3
	s_nop 1
	v_cndmask_b32_e32 v2, v2, v6, vcc
	v_mul_lo_u32 v5, v3, v2
	v_add_u32_e32 v3, v5, v3
	v_cmp_ne_u32_e32 vcc, v4, v3
	s_and_saveexec_b64 s[8:9], vcc
	s_xor_b64 s[8:9], exec, s[8:9]
	s_cbranch_execz .LBB0_588
	s_waitcnt lgkmcnt(0)
	v_add_u32_e32 v2, 1, v2
	v_mul_lo_u32 v2, v2, v1
	v_add_u32_e32 v2, -1, v2
	v_mov_b32_e32 v1, 0x3000
	global_load_dword v1, v1, s[52:53] offset:1024 sc1
	s_add_u32 s12, s52, 0x3400
	s_addc_u32 s13, s53, 0
	s_waitcnt vmcnt(0)
	v_cmp_le_u32_e32 vcc, v1, v2
	s_and_saveexec_b64 s[10:11], vcc
	s_cbranch_execz .LBB0_587
	s_mov_b32 s24, 1
	s_mov_b64 s[14:15], 0
	v_mov_b32_e32 v1, 0
	s_branch .LBB0_578

; __device__ __forceinline__ unsigned xb_ld(unsigned* p)              { return __hip_atomic_load(p, __ATOMIC_RELAXED, __HIP_MEMORY_SCOPE_AGENT); }
; __device__ __forceinline__ unsigned xb_add(unsigned* p, unsigned v) { return __hip_atomic_fetch_add(p, v, __ATOMIC_RELAXED, __HIP_MEMORY_SCOPE_AGENT); }
; #define XB_SPIN(cond, bar) do { unsigned _sp = 0; while (cond) { __builtin_amdgcn_s_sleep(1); \
;     if ((++_sp & 255u) == 0u) { if (xb_ld(&(bar)[XB_TMO])) break; if (_sp > XB_SPIN_CAP) { atomicAdd(&(bar)[XB_TMO], 1u); break; } } } } while (0)
; __device__ __forceinline__ void xcd_barrier(const XcdBarrier& b) {
;     ...
;         if (old + 1u == (gen + 1u) * nloc) {
;             __builtin_amdgcn_fence(__ATOMIC_RELEASE, "agent");
;             asm volatile("s_waitcnt vmcnt(0)" ::: "memory");
;             const unsigned og = xb_add(&bar[XB_TOP], 1u);
;             const unsigned tg = og / nx;
;             if (og + 1u == (tg + 1u) * nx) xb_add(&bar[XB_TOPGEN], 1u);
;             else XB_SPIN(xb_ld(&bar[XB_TOPGEN]) == tg, bar);
;             __builtin_amdgcn_fence(__ATOMIC_ACQUIRE, "agent");
.LBB0_591:
	s_or_b64 exec, exec, s[10:11]
	v_cvt_f32_u32_e32 v4, v1
	s_waitcnt vmcnt(0)
	v_readfirstlane_b32 s8, v3
	s_add_u32 s10, s52, 0x3500
	s_addc_u32 s11, s53, 0
	v_rcp_iflag_f32_e32 v4, v4
	v_add_u32_e32 v2, s8, v2
	v_add_u32_e32 v5, 1, v2
	s_mov_b64 s[12:13], -1
	v_mul_f32_e32 v3, 0x4f7ffffe, v4
	v_cvt_u32_f32_e32 v3, v3
	v_sub_u32_e32 v4, 0, v1
	v_mul_lo_u32 v4, v4, v3
	v_mul_hi_u32 v4, v3, v4
	v_add_u32_e32 v3, v3, v4
	v_mul_hi_u32 v3, v2, v3
	v_mul_lo_u32 v4, v3, v1
	v_sub_u32_e32 v2, v2, v4
	v_add_u32_e32 v6, 1, v3
	v_cmp_ge_u32_e32 vcc, v2, v1
	v_sub_u32_e32 v4, v2, v1
	s_nop 0
	v_cndmask_b32_e32 v3, v3, v6, vcc
	v_cndmask_b32_e32 v2, v2, v4, vcc
	v_add_u32_e32 v4, 1, v3
	v_cmp_ge_u32_e32 vcc, v2, v1
	s_nop 1
	v_cndmask_b32_e32 v4, v3, v4, vcc
	v_mul_lo_u32 v2, v1, v4
	v_add_u32_e32 v1, v2, v1
	v_cmp_ne_u32_e32 vcc, v5, v1
	v_mov_b32_e32 v4, v1
	v_mov_b64_e32 v[2:3], s[10:11]
	s_and_saveexec_b64 s[8:9], vcc
	s_cbranch_execz .LBB0_603
	v_mov_b32_e32 v1, 0
	global_load_dword v2, v1, s[10:11] offset:-256 sc1
	s_mov_b64 s[16:17], 0
	s_waitcnt vmcnt(0)
	v_cmp_lt_u32_e32 vcc, v2, v4
	s_and_saveexec_b64 s[14:15], vcc
	s_cbranch_execz .LBB0_602
	s_add_u32 s12, s52, 0x200
	s_addc_u32 s13, s53, 0
	s_mov_b32 s26, 1
	s_branch .LBB0_595

; __device__ __forceinline__ unsigned xb_ld(unsigned* p)              { return __hip_atomic_load(p, __ATOMIC_RELAXED, __HIP_MEMORY_SCOPE_AGENT); }
; __device__ __forceinline__ unsigned xb_add(unsigned* p, unsigned v) { return __hip_atomic_fetch_add(p, v, __ATOMIC_RELAXED, __HIP_MEMORY_SCOPE_AGENT); }
; #define XB_SPIN(cond, bar) do { unsigned _sp = 0; while (cond) { __builtin_amdgcn_s_sleep(1); \
;     if ((++_sp & 255u) == 0u) { if (xb_ld(&(bar)[XB_TMO])) break; if (_sp > XB_SPIN_CAP) { atomicAdd(&(bar)[XB_TMO], 1u); break; } } } } while (0)
; __device__ __forceinline__ void xcd_barrier(const XcdBarrier& b) {
;     ...
;             const unsigned og = xb_add(&bar[XB_TOP], 1u);
;             const unsigned tg = og / nx;
;             if (og + 1u == (tg + 1u) * nx) xb_add(&bar[XB_TOPGEN], 1u);
;             else XB_SPIN(xb_ld(&bar[XB_TOPGEN]) == tg, bar);
.LBB0_597:
	global_load_dword v2, v1, s[10:11] offset:-256 sc1
	s_add_i32 s26, s26, 1
	s_mov_b64 s[20:21], -1
	s_waitcnt vmcnt(0)
	v_cmp_ge_u32_e32 vcc, v2, v4
	s_orn2_b64 s[24:25], vcc, exec
	s_branch .LBB0_594
